# v013 + nt on phase-0 XN dwordx2 stores
# baseline (speedup 1.0000x reference)
; __device__ __forceinline__ void phase0(const Args& a, LAS unsigned char* lds, int bid, int G) {
;     ...
;     for (int m = gw; m < T; m += NGW) {
;         const f32x4* xr = (const f32x4*)(a.x + (size_t)m * DM) + lane;
;         f32x4 v[16]; float s = 0.f;
; #pragma unroll
;         for (int j = 0; j < 16; ++j) { v[j] = xr[64 * j]; s += (v[j][0] * v[j][0] + v[j][1] * v[j][1]) + (v[j][2] * v[j][2] + v[j][3] * v[j][3]); }
;         const float rstd = 1.0f / sqrtf(wave_sum(s) * (1.0f / DM) + EPS);
.LBB0_50:
	global_load_dwordx4 v[12:15], v[92:93], off nt
	global_load_dwordx4 v[8:11], v[92:93], off offset:1024 nt
	global_load_dwordx4 v[4:7], v[92:93], off offset:2048 nt
	global_load_dwordx4 v[0:3], v[92:93], off offset:3072 nt
	v_add_co_u32_e32 v94, vcc, s7, v92
	s_lshr_b32 s0, s76, 3
	s_nop 0
	v_addc_co_u32_e32 v95, vcc, 0, v93, vcc
	v_add_co_u32_e32 v96, vcc, s12, v92
	s_ashr_i32 s15, s76, 1
	s_nop 0
	v_addc_co_u32_e32 v97, vcc, 0, v93, vcc
	v_add_co_u32_e32 v98, vcc, s13, v92
	s_and_b32 s1, s10, 0x3c0
	s_nop 0
	v_addc_co_u32_e32 v99, vcc, 0, v93, vcc
	global_load_dwordx4 v[112:115], v[66:67], off
	global_load_dwordx4 v[60:63], v[96:97], off offset:-4096 nt
	global_load_dwordx4 v[52:55], v[94:95], off offset:2048 nt
	global_load_dwordx4 v[56:59], v[94:95], off offset:1024 nt
	global_load_dwordx4 v[48:51], v[94:95], off offset:3072 nt
	global_load_dwordx4 v[40:43], v[96:97], off offset:1024 nt
	global_load_dwordx4 v[44:47], v[96:97], off nt
	global_load_dwordx4 v[36:39], v[96:97], off offset:2048 nt
	global_load_dwordx4 v[28:31], v[98:99], off nt
	global_load_dwordx4 v[32:35], v[96:97], off offset:3072 nt
	global_load_dwordx4 v[24:27], v[98:99], off offset:1024 nt
	global_load_dwordx4 v[16:19], v[98:99], off offset:3072 nt
	global_load_dwordx4 v[20:23], v[98:99], off offset:2048 nt
	s_lshr_b32 s16, s10, 4
	v_and_or_b32 v64, s0, 14, v106
	s_andn2_b32 s15, s15, 63
	v_or_b32_e32 v94, s1, v107
	s_and_b32 s0, s16, 32
	v_lshlrev_b32_e32 v64, 10, v64
	v_or_b32_e32 v96, s15, v108
	v_bitop3_b32 v64, v94, v64, s0 bitop3:0xde
	v_ashrrev_i32_e32 v97, 31, v96
	v_lshl_add_u64 v[94:95], s[30:31], 0, v[64:65]
	v_lshlrev_b64 v[98:99], 14, v[96:97]
	v_lshl_add_u64 v[98:99], v[94:95], 0, v[98:99]
	s_add_i32 s76, s76, s6
	s_add_i32 s10, s10, s11
	v_lshl_add_u64 v[92:93], v[92:93], 0, s[8:9]
	s_cmpk_gt_i32 s76, 0x3fff
	s_waitcnt vmcnt(16)
	v_pk_mul_f32 v[116:117], v[14:15], v[14:15]
	v_pk_mul_f32 v[118:119], v[12:13], v[12:13]
	s_waitcnt vmcnt(15)
	v_pk_mul_f32 v[120:121], v[10:11], v[10:11]
	v_pk_mul_f32 v[122:123], v[8:9], v[8:9]
	v_pk_mov_b32 v[126:127], v[118:119], v[116:117] op_sel:[1,0]
	v_mov_b32_e32 v119, v117
	v_pk_mov_b32 v[116:117], v[122:123], v[120:121] op_sel:[1,0]
	v_mov_b32_e32 v123, v121
	s_waitcnt vmcnt(14)
	v_mul_f32_e32 v64, v5, v5
	v_mul_f32_e32 v124, v7, v7
	v_pk_add_f32 v[118:119], v[126:127], v[118:119]
	v_pk_add_f32 v[116:117], v[116:117], v[122:123]
	s_waitcnt vmcnt(13)
	v_mul_f32_e32 v97, v0, v0
	v_mul_f32_e32 v157, v1, v1
	v_mul_f32_e32 v133, v2, v2
	v_mul_f32_e32 v139, v3, v3
	v_pk_fma_f32 v[120:121], v[4:5], v[4:5], v[64:65] op_sel_hi:[1,1,0]
	v_pk_fma_f32 v[124:125], v[6:7], v[6:7], v[124:125] op_sel_hi:[1,1,0]
	v_pk_add_f32 v[118:119], v[118:119], v[118:119] op_sel:[0,1] op_sel_hi:[1,0]
	v_pk_add_f32 v[116:117], v[116:117], v[116:117] op_sel:[0,1] op_sel_hi:[1,0]
	s_waitcnt vmcnt(11)
	v_pk_mul_f32 v[128:129], v[62:63], v[62:63]
	v_pk_mul_f32 v[130:131], v[60:61], v[60:61]
	v_mov_b32_e32 v121, v133
	v_mov_b32_e32 v125, v139
	v_mov_b32_e32 v119, v97
	v_mov_b32_e32 v117, v157
	v_pk_mov_b32 v[122:123], v[130:131], v[128:129] op_sel:[1,0]
	v_mov_b32_e32 v131, v129
	v_pk_add_f32 v[120:121], v[120:121], v[124:125]
	v_pk_add_f32 v[116:117], v[118:119], v[116:117]
	s_waitcnt vmcnt(9)
	v_mul_f32_e32 v64, v57, v57
	v_mul_f32_e32 v132, v59, v59
	v_pk_add_f32 v[122:123], v[122:123], v[130:131]
	v_pk_add_f32 v[116:117], v[116:117], v[120:121]
	v_mul_f32_e32 v158, v52, v52
	v_mul_f32_e32 v159, v53, v53
	v_mul_f32_e32 v160, v54, v54
	v_mul_f32_e32 v161, v55, v55
	v_pk_fma_f32 v[126:127], v[56:57], v[56:57], v[64:65] op_sel_hi:[1,1,0]
	v_pk_fma_f32 v[128:129], v[58:59], v[58:59], v[132:133] op_sel_hi:[1,1,0]
	v_pk_add_f32 v[122:123], v[122:123], v[122:123] op_sel:[0,1] op_sel_hi:[1,0]
	v_pk_add_f32 v[116:117], v[116:117], v[116:117] op_sel:[0,1] op_sel_hi:[1,0]
	s_waitcnt vmcnt(8)
	v_pk_mul_f32 v[134:135], v[50:51], v[50:51]
	v_pk_mul_f32 v[136:137], v[48:49], v[48:49]
	v_mov_b32_e32 v127, v160
	v_mov_b32_e32 v129, v161
	v_mov_b32_e32 v123, v159
	v_mov_b32_e32 v117, v158
	v_pk_mov_b32 v[132:133], v[136:137], v[134:135] op_sel:[1,0]
	v_mov_b32_e32 v137, v135
	v_pk_add_f32 v[126:127], v[126:127], v[128:129]
	v_pk_add_f32 v[116:117], v[116:117], v[122:123]
	s_waitcnt vmcnt(6)
	v_mul_f32_e32 v138, v45, v45
	v_mul_f32_e32 v140, v47, v47
	v_pk_add_f32 v[124:125], v[132:133], v[136:137]
	v_pk_add_f32 v[116:117], v[116:117], v[126:127]
	v_mul_f32_e32 v162, v40, v40
	v_mul_f32_e32 v163, v41, v41
	v_mul_f32_e32 v164, v42, v42
	v_mul_f32_e32 v165, v43, v43
	v_pk_fma_f32 v[134:135], v[44:45], v[44:45], v[138:139] op_sel_hi:[1,1,0]
	v_pk_fma_f32 v[138:139], v[46:47], v[46:47], v[140:141] op_sel_hi:[1,1,0]
	v_pk_add_f32 v[124:125], v[124:125], v[124:125] op_sel:[0,1] op_sel_hi:[1,0]
	v_pk_add_f32 v[116:117], v[116:117], v[116:117] op_sel:[0,1] op_sel_hi:[1,0]
	s_waitcnt vmcnt(5)
	v_pk_mul_f32 v[142:143], v[38:39], v[38:39]
	v_pk_mul_f32 v[144:145], v[36:37], v[36:37]
	v_mov_b32_e32 v135, v164
	v_mov_b32_e32 v139, v165
	v_mov_b32_e32 v125, v163
	v_mov_b32_e32 v117, v162
	v_pk_mov_b32 v[140:141], v[144:145], v[142:143] op_sel:[1,0]
	v_mov_b32_e32 v145, v143
	v_pk_add_f32 v[128:129], v[134:135], v[138:139]
	v_pk_add_f32 v[116:117], v[116:117], v[124:125]
	s_waitcnt vmcnt(3)
	v_mul_f32_e32 v146, v33, v33
	v_mul_f32_e32 v148, v35, v35
	v_pk_add_f32 v[130:131], v[140:141], v[144:145]
	v_pk_add_f32 v[116:117], v[116:117], v[128:129]
	v_mul_f32_e32 v166, v28, v28
	v_mul_f32_e32 v167, v29, v29
	v_mul_f32_e32 v168, v30, v30
	v_mul_f32_e32 v169, v31, v31
	v_pk_fma_f32 v[142:143], v[32:33], v[32:33], v[146:147] op_sel_hi:[1,1,0]
	v_pk_fma_f32 v[146:147], v[34:35], v[34:35], v[148:149] op_sel_hi:[1,1,0]
	v_pk_add_f32 v[130:131], v[130:131], v[130:131] op_sel:[0,1] op_sel_hi:[1,0]
	v_pk_add_f32 v[116:117], v[116:117], v[116:117] op_sel:[0,1] op_sel_hi:[1,0]
	s_waitcnt vmcnt(2)
; __device__ __forceinline__ unsigned pk2(float lo, float hi) { return __builtin_bit_cast(unsigned, __builtin_convertvector((f32x2){lo, hi}, bf16x2_t)); }
; __device__ __forceinline__ void phase0(const Args& a, LAS unsigned char* lds, int bid, int G) {
;     ...
;         for (int j = 0; j < 16; ++j) { v[j] = xr[64 * j]; s += (v[j][0] * v[j][0] + v[j][1] * v[j][1]) + (v[j][2] * v[j][2] + v[j][3] * v[j][3]); }
;         const float rstd = 1.0f / sqrtf(wave_sum(s) * (1.0f / DM) + EPS);
;         char* xo = (char*)XN;
; #pragma unroll
;         for (int j = 0; j < 16; ++j) { const f32x4 w = *((const f32x4*)a.norm_w + lane + 64 * j);
;             u32x2 p; p.x = pk2(v[j][0] * rstd * w[0], v[j][1] * rstd * w[1]); p.y = pk2(v[j][2] * rstd * w[2], v[j][3] * rstd * w[3]); *(u32x2*)(xo + tiled_off(m, 4 * lane + 256 * j)) = p; }
	v_pk_mul_f32 v[150:151], v[26:27], v[26:27]
	v_pk_mul_f32 v[152:153], v[24:25], v[24:25]
	v_mov_b32_e32 v143, v168
	v_mov_b32_e32 v147, v169
	v_mov_b32_e32 v131, v167
	v_mov_b32_e32 v117, v166
	v_pk_mov_b32 v[148:149], v[152:153], v[150:151] op_sel:[1,0]
	v_mov_b32_e32 v153, v151
	v_pk_add_f32 v[134:135], v[142:143], v[146:147]
	v_pk_add_f32 v[116:117], v[116:117], v[130:131]
	s_waitcnt vmcnt(0)
	v_mul_f32_e32 v154, v21, v21
	v_mul_f32_e32 v156, v23, v23
	v_pk_add_f32 v[132:133], v[148:149], v[152:153]
	v_pk_add_f32 v[116:117], v[116:117], v[134:135]
	v_mul_f32_e32 v170, v16, v16
	v_mul_f32_e32 v171, v17, v17
	v_mul_f32_e32 v172, v18, v18
	v_mul_f32_e32 v173, v19, v19
	v_pk_fma_f32 v[150:151], v[20:21], v[20:21], v[154:155] op_sel_hi:[1,1,0]
	v_pk_fma_f32 v[154:155], v[22:23], v[22:23], v[156:157] op_sel_hi:[1,1,0]
	v_pk_add_f32 v[132:133], v[132:133], v[132:133] op_sel:[0,1] op_sel_hi:[1,0]
	v_pk_add_f32 v[116:117], v[116:117], v[116:117] op_sel:[0,1] op_sel_hi:[1,0]
	v_mov_b32_e32 v151, v172
	v_mov_b32_e32 v155, v173
	v_mov_b32_e32 v133, v171
	v_mov_b32_e32 v117, v170
	v_pk_add_f32 v[136:137], v[150:151], v[154:155]
	v_pk_add_f32 v[116:117], v[116:117], v[132:133]
	s_nop 0
	v_pk_add_f32 v[116:117], v[116:117], v[136:137]
	s_nop 0
	v_add_f32_e32 v64, v116, v117
	ds_bpermute_b32 v97, v100, v64
	s_waitcnt lgkmcnt(0)
	v_add_f32_e32 v64, v64, v97
	ds_bpermute_b32 v97, v101, v64
	s_waitcnt lgkmcnt(0)
	v_add_f32_e32 v64, v64, v97
	ds_bpermute_b32 v97, v102, v64
	s_waitcnt lgkmcnt(0)
	v_add_f32_e32 v64, v64, v97
	ds_bpermute_b32 v97, v103, v64
	s_waitcnt lgkmcnt(0)
	v_add_f32_e32 v64, v64, v97
	ds_bpermute_b32 v97, v104, v64
	s_waitcnt lgkmcnt(0)
	v_add_f32_e32 v64, v64, v97
	ds_bpermute_b32 v97, v105, v64
	s_waitcnt lgkmcnt(0)
	v_add_f32_e32 v64, v64, v97
	v_fmamk_f32 v64, v64, 0x39800000, v110
	v_mul_f32_e32 v97, 0x4f800000, v64
	v_cmp_gt_f32_e32 vcc, s14, v64
	s_nop 1
	v_cndmask_b32_e32 v64, v64, v97, vcc
	v_sqrt_f32_e32 v97, v64
	s_nop 0
	v_add_u32_e32 v116, -1, v97
	v_add_u32_e32 v117, 1, v97
	v_fma_f32 v118, -v116, v97, v64
	v_fma_f32 v119, -v117, v97, v64
	v_cmp_ge_f32_e64 s[0:1], 0, v118
	s_nop 1
	v_cndmask_b32_e64 v97, v97, v116, s[0:1]
	v_cmp_lt_f32_e64 s[0:1], 0, v119
	s_nop 1
	v_cndmask_b32_e64 v97, v97, v117, s[0:1]
	v_mul_f32_e32 v116, 0x37800000, v97
	v_cndmask_b32_e32 v97, v97, v116, vcc
	v_cmp_class_f32_e32 vcc, v64, v111
	s_nop 1
	v_cndmask_b32_e32 v64, v97, v64, vcc
	v_div_scale_f32 v97, s[0:1], v64, v64, 1.0
	v_rcp_f32_e32 v117, v97
	v_div_scale_f32 v116, vcc, 1.0, v64, 1.0
	v_fma_f32 v118, -v97, v117, 1.0
	v_fmac_f32_e32 v117, v118, v117
	v_mul_f32_e32 v118, v116, v117
	v_fma_f32 v119, -v97, v118, v116
	v_fmac_f32_e32 v118, v119, v117
	v_fma_f32 v97, -v97, v118, v116
	v_div_fmas_f32 v97, v97, v117, v118
	v_div_fixup_f32 v64, v97, v64, 1.0
	v_pk_mul_f32 v[12:13], v[12:13], v[64:65] op_sel_hi:[1,0]
	v_pk_mul_f32 v[14:15], v[14:15], v[64:65] op_sel_hi:[1,0]
	v_pk_mul_f32 v[12:13], v[112:113], v[12:13]
	v_pk_mul_f32 v[14:15], v[114:115], v[14:15]
	v_cvt_pk_bf16_f32 v12, v12, v13
	v_cvt_pk_bf16_f32 v13, v14, v15
	global_store_dwordx2 v[98:99], v[12:13], off nt
	global_load_dwordx4 v[12:15], v[66:67], off offset:1024
	v_or_b32_e32 v98, 4, v96
	v_ashrrev_i32_e32 v99, 31, v98
	v_pk_mul_f32 v[8:9], v[8:9], v[64:65] op_sel_hi:[1,0]
	v_pk_mul_f32 v[10:11], v[10:11], v[64:65] op_sel_hi:[1,0]
	v_lshlrev_b64 v[98:99], 14, v[98:99]
	v_lshl_add_u64 v[98:99], v[94:95], 0, v[98:99]
	v_pk_mul_f32 v[4:5], v[4:5], v[64:65] op_sel_hi:[1,0]
	v_pk_mul_f32 v[6:7], v[6:7], v[64:65] op_sel_hi:[1,0]
	v_pk_mul_f32 v[0:1], v[0:1], v[64:65] op_sel_hi:[1,0]
	v_pk_mul_f32 v[2:3], v[2:3], v[64:65] op_sel_hi:[1,0]
	s_waitcnt vmcnt(0)
	v_pk_mul_f32 v[8:9], v[12:13], v[8:9]
	v_pk_mul_f32 v[10:11], v[14:15], v[10:11]
	v_cvt_pk_bf16_f32 v8, v8, v9
	v_cvt_pk_bf16_f32 v9, v10, v11
	global_store_dwordx2 v[98:99], v[8:9], off nt
	global_load_dwordx4 v[8:11], v[66:67], off offset:2048
	v_or_b32_e32 v12, 8, v96
	v_ashrrev_i32_e32 v13, 31, v12
	v_lshlrev_b64 v[12:13], 14, v[12:13]
	v_lshl_add_u64 v[12:13], v[94:95], 0, v[12:13]
	s_waitcnt vmcnt(0)
	v_pk_mul_f32 v[4:5], v[8:9], v[4:5]
	v_pk_mul_f32 v[6:7], v[10:11], v[6:7]
	v_cvt_pk_bf16_f32 v4, v4, v5
	v_cvt_pk_bf16_f32 v5, v6, v7
	global_store_dwordx2 v[12:13], v[4:5], off nt
	global_load_dwordx4 v[4:7], v[66:67], off offset:3072
	v_or_b32_e32 v8, 12, v96
	v_ashrrev_i32_e32 v9, 31, v8
	v_lshlrev_b64 v[8:9], 14, v[8:9]
	v_lshl_add_u64 v[8:9], v[94:95], 0, v[8:9]
	s_waitcnt vmcnt(0)
	v_pk_mul_f32 v[0:1], v[4:5], v[0:1]
	v_pk_mul_f32 v[2:3], v[6:7], v[2:3]
	v_cvt_pk_bf16_f32 v0, v0, v1
	v_cvt_pk_bf16_f32 v1, v2, v3
	global_store_dwordx2 v[8:9], v[0:1], off nt
	global_load_dwordx4 v[0:3], v[68:69], off
	v_or_b32_e32 v4, 16, v96
	v_ashrrev_i32_e32 v5, 31, v4
	v_pk_mul_f32 v[6:7], v[60:61], v[64:65] op_sel_hi:[1,0]
	v_pk_mul_f32 v[8:9], v[62:63], v[64:65] op_sel_hi:[1,0]
	v_lshlrev_b64 v[4:5], 14, v[4:5]
	v_lshl_add_u64 v[4:5], v[94:95], 0, v[4:5]
	s_waitcnt vmcnt(0)
	v_pk_mul_f32 v[0:1], v[0:1], v[6:7]
	v_pk_mul_f32 v[2:3], v[2:3], v[8:9]
	v_cvt_pk_bf16_f32 v0, v0, v1
	v_cvt_pk_bf16_f32 v1, v2, v3
	global_store_dwordx2 v[4:5], v[0:1], off nt
	global_load_dwordx4 v[0:3], v[70:71], off
	v_or_b32_e32 v4, 20, v96
	v_ashrrev_i32_e32 v5, 31, v4
	v_pk_mul_f32 v[6:7], v[56:57], v[64:65] op_sel_hi:[1,0]
	v_pk_mul_f32 v[8:9], v[58:59], v[64:65] op_sel_hi:[1,0]
	v_lshlrev_b64 v[4:5], 14, v[4:5]
	v_lshl_add_u64 v[4:5], v[94:95], 0, v[4:5]
	s_waitcnt vmcnt(0)
; __device__ __forceinline__ unsigned pk2(float lo, float hi) { return __builtin_bit_cast(unsigned, __builtin_convertvector((f32x2){lo, hi}, bf16x2_t)); }
; __device__ __forceinline__ void phase0(const Args& a, LAS unsigned char* lds, int bid, int G) {
;     ...
;         for (int j = 0; j < 16; ++j) { const f32x4 w = *((const f32x4*)a.norm_w + lane + 64 * j);
;             u32x2 p; p.x = pk2(v[j][0] * rstd * w[0], v[j][1] * rstd * w[1]); p.y = pk2(v[j][2] * rstd * w[2], v[j][3] * rstd * w[3]); *(u32x2*)(xo + tiled_off(m, 4 * lane + 256 * j)) = p; }
	v_pk_mul_f32 v[0:1], v[6:7], v[0:1]
	v_pk_mul_f32 v[2:3], v[8:9], v[2:3]
	v_cvt_pk_bf16_f32 v0, v0, v1
	v_cvt_pk_bf16_f32 v1, v2, v3
	global_store_dwordx2 v[4:5], v[0:1], off nt
	global_load_dwordx4 v[0:3], v[72:73], off
	v_or_b32_e32 v4, 24, v96
	v_ashrrev_i32_e32 v5, 31, v4
	v_pk_mul_f32 v[6:7], v[52:53], v[64:65] op_sel_hi:[1,0]
	v_pk_mul_f32 v[8:9], v[54:55], v[64:65] op_sel_hi:[1,0]
	v_lshlrev_b64 v[4:5], 14, v[4:5]
	v_lshl_add_u64 v[4:5], v[94:95], 0, v[4:5]
	s_waitcnt vmcnt(0)
	v_pk_mul_f32 v[0:1], v[6:7], v[0:1]
	v_pk_mul_f32 v[2:3], v[8:9], v[2:3]
	v_cvt_pk_bf16_f32 v0, v0, v1
	v_cvt_pk_bf16_f32 v1, v2, v3
	global_store_dwordx2 v[4:5], v[0:1], off nt
	global_load_dwordx4 v[0:3], v[74:75], off
	v_or_b32_e32 v4, 28, v96
	v_ashrrev_i32_e32 v5, 31, v4
	v_pk_mul_f32 v[6:7], v[48:49], v[64:65] op_sel_hi:[1,0]
	v_pk_mul_f32 v[8:9], v[50:51], v[64:65] op_sel_hi:[1,0]
	v_lshlrev_b64 v[4:5], 14, v[4:5]
	v_lshl_add_u64 v[4:5], v[94:95], 0, v[4:5]
	s_waitcnt vmcnt(0)
	v_pk_mul_f32 v[0:1], v[6:7], v[0:1]
	v_pk_mul_f32 v[2:3], v[8:9], v[2:3]
	v_cvt_pk_bf16_f32 v0, v0, v1
	v_cvt_pk_bf16_f32 v1, v2, v3
	global_store_dwordx2 v[4:5], v[0:1], off nt
	global_load_dwordx4 v[0:3], v[76:77], off
	v_or_b32_e32 v4, 32, v96
	v_ashrrev_i32_e32 v5, 31, v4
	v_pk_mul_f32 v[6:7], v[44:45], v[64:65] op_sel_hi:[1,0]
	v_pk_mul_f32 v[8:9], v[46:47], v[64:65] op_sel_hi:[1,0]
	v_lshlrev_b64 v[4:5], 14, v[4:5]
	v_lshl_add_u64 v[4:5], v[94:95], 0, v[4:5]
	s_waitcnt vmcnt(0)
	v_pk_mul_f32 v[0:1], v[6:7], v[0:1]
	v_pk_mul_f32 v[2:3], v[8:9], v[2:3]
	v_cvt_pk_bf16_f32 v0, v0, v1
	v_cvt_pk_bf16_f32 v1, v2, v3
	global_store_dwordx2 v[4:5], v[0:1], off nt
	global_load_dwordx4 v[0:3], v[78:79], off
	v_or_b32_e32 v4, 36, v96
	v_ashrrev_i32_e32 v5, 31, v4
	v_pk_mul_f32 v[6:7], v[40:41], v[64:65] op_sel_hi:[1,0]
	v_pk_mul_f32 v[8:9], v[42:43], v[64:65] op_sel_hi:[1,0]
	v_lshlrev_b64 v[4:5], 14, v[4:5]
	v_lshl_add_u64 v[4:5], v[94:95], 0, v[4:5]
	s_waitcnt vmcnt(0)
	v_pk_mul_f32 v[0:1], v[6:7], v[0:1]
	v_pk_mul_f32 v[2:3], v[8:9], v[2:3]
	v_cvt_pk_bf16_f32 v0, v0, v1
	v_cvt_pk_bf16_f32 v1, v2, v3
	global_store_dwordx2 v[4:5], v[0:1], off nt
	global_load_dwordx4 v[0:3], v[80:81], off
	v_or_b32_e32 v4, 40, v96
	v_ashrrev_i32_e32 v5, 31, v4
	v_pk_mul_f32 v[6:7], v[36:37], v[64:65] op_sel_hi:[1,0]
	v_pk_mul_f32 v[8:9], v[38:39], v[64:65] op_sel_hi:[1,0]
	v_lshlrev_b64 v[4:5], 14, v[4:5]
	v_lshl_add_u64 v[4:5], v[94:95], 0, v[4:5]
	s_waitcnt vmcnt(0)
	v_pk_mul_f32 v[0:1], v[6:7], v[0:1]
	v_pk_mul_f32 v[2:3], v[8:9], v[2:3]
	v_cvt_pk_bf16_f32 v0, v0, v1
	v_cvt_pk_bf16_f32 v1, v2, v3
	global_store_dwordx2 v[4:5], v[0:1], off nt
	global_load_dwordx4 v[0:3], v[82:83], off
	v_or_b32_e32 v4, 44, v96
	v_ashrrev_i32_e32 v5, 31, v4
	v_pk_mul_f32 v[6:7], v[32:33], v[64:65] op_sel_hi:[1,0]
	v_pk_mul_f32 v[8:9], v[34:35], v[64:65] op_sel_hi:[1,0]
	v_lshlrev_b64 v[4:5], 14, v[4:5]
	v_lshl_add_u64 v[4:5], v[94:95], 0, v[4:5]
	s_waitcnt vmcnt(0)
	v_pk_mul_f32 v[0:1], v[6:7], v[0:1]
	v_pk_mul_f32 v[2:3], v[8:9], v[2:3]
	v_cvt_pk_bf16_f32 v0, v0, v1
	v_cvt_pk_bf16_f32 v1, v2, v3
	global_store_dwordx2 v[4:5], v[0:1], off nt
	global_load_dwordx4 v[0:3], v[84:85], off
	v_or_b32_e32 v4, 48, v96
	v_ashrrev_i32_e32 v5, 31, v4
	v_pk_mul_f32 v[6:7], v[28:29], v[64:65] op_sel_hi:[1,0]
	v_pk_mul_f32 v[8:9], v[30:31], v[64:65] op_sel_hi:[1,0]
	v_lshlrev_b64 v[4:5], 14, v[4:5]
	v_lshl_add_u64 v[4:5], v[94:95], 0, v[4:5]
	s_waitcnt vmcnt(0)
	v_pk_mul_f32 v[0:1], v[6:7], v[0:1]
	v_pk_mul_f32 v[2:3], v[8:9], v[2:3]
	v_cvt_pk_bf16_f32 v0, v0, v1
	v_cvt_pk_bf16_f32 v1, v2, v3
	global_store_dwordx2 v[4:5], v[0:1], off nt
	global_load_dwordx4 v[0:3], v[86:87], off
	v_or_b32_e32 v4, 52, v96
	v_ashrrev_i32_e32 v5, 31, v4
	v_pk_mul_f32 v[6:7], v[24:25], v[64:65] op_sel_hi:[1,0]
	v_pk_mul_f32 v[8:9], v[26:27], v[64:65] op_sel_hi:[1,0]
	v_lshlrev_b64 v[4:5], 14, v[4:5]
	v_lshl_add_u64 v[4:5], v[94:95], 0, v[4:5]
	s_waitcnt vmcnt(0)
	v_pk_mul_f32 v[0:1], v[6:7], v[0:1]
	v_pk_mul_f32 v[2:3], v[8:9], v[2:3]
	v_cvt_pk_bf16_f32 v0, v0, v1
	v_cvt_pk_bf16_f32 v1, v2, v3
	global_store_dwordx2 v[4:5], v[0:1], off nt
	global_load_dwordx4 v[0:3], v[88:89], off
	v_or_b32_e32 v4, 56, v96
	v_ashrrev_i32_e32 v5, 31, v4
	v_pk_mul_f32 v[6:7], v[20:21], v[64:65] op_sel_hi:[1,0]
	v_pk_mul_f32 v[8:9], v[22:23], v[64:65] op_sel_hi:[1,0]
	v_lshlrev_b64 v[4:5], 14, v[4:5]
	v_lshl_add_u64 v[4:5], v[94:95], 0, v[4:5]
	s_waitcnt vmcnt(0)
	v_pk_mul_f32 v[0:1], v[6:7], v[0:1]
	v_pk_mul_f32 v[2:3], v[8:9], v[2:3]
	v_cvt_pk_bf16_f32 v0, v0, v1
	v_cvt_pk_bf16_f32 v1, v2, v3
	global_store_dwordx2 v[4:5], v[0:1], off nt
	global_load_dwordx4 v[0:3], v[90:91], off
	v_or_b32_e32 v4, s15, v109
	v_ashrrev_i32_e32 v5, 31, v4
	v_pk_mul_f32 v[6:7], v[16:17], v[64:65] op_sel_hi:[1,0]
	v_pk_mul_f32 v[8:9], v[18:19], v[64:65] op_sel_hi:[1,0]
	v_lshlrev_b64 v[4:5], 14, v[4:5]
	v_lshl_add_u64 v[4:5], v[94:95], 0, v[4:5]
	s_waitcnt vmcnt(0)
	v_pk_mul_f32 v[0:1], v[6:7], v[0:1]
	v_pk_mul_f32 v[2:3], v[8:9], v[2:3]
	v_cvt_pk_bf16_f32 v0, v0, v1
	v_cvt_pk_bf16_f32 v1, v2, v3
	global_store_dwordx2 v[4:5], v[0:1], off nt
	s_cbranch_scc0 .LBB0_50
